# saddr LDS-DMA + removed 128 redundant NaN-canonicalising v_max in the MLP-up relu^2 epilogue (store-data WAR wait states re-padded)
# speedup vs baseline: 1.0028x; 1.0028x over previous
.LBB0_1218:
	v_lshl_add_u32 v150, s26, 8, v152
	s_lshl_b32 s19, s27, 8
	v_max_f32_e32 v129, 0, v129
	v_max_f32_e32 v128, 0, v128
	s_or_b32 s19, s19, s44
	v_ashrrev_i32_e32 v151, 31, v150
	v_max_f32_e32 v125, 0, v125
	v_max_f32_e32 v124, 0, v124
	v_pk_mul_f32 v[128:129], v[128:129], v[128:129]
	v_max_f32_e32 v127, 0, v127
	v_max_f32_e32 v126, 0, v126
	v_max_f32_e32 v123, 0, v123
	v_max_f32_e32 v122, 0, v122
	v_pk_mul_f32 v[160:161], v[124:125], v[124:125]
	v_cvt_pk_bf16_f32 v125, v128, v129
	v_lshlrev_b64 v[128:129], 1, v[150:151]
	s_ashr_i32 s26, s19, 6
	v_pk_mul_f32 v[126:127], v[126:127], v[126:127]
	v_pk_mul_f32 v[122:123], v[122:123], v[122:123]
	v_and_b32_e32 v128, 0xffffff00, v128
	s_ashr_i32 s27, s26, 31
	v_cvt_pk_bf16_f32 v124, v126, v127
	v_cvt_pk_bf16_f32 v126, v122, v123
	v_lshl_add_u64 v[122:123], v[128:129], 0, s[26:27]
	v_lshlrev_b64 v[122:123], 14, v[122:123]
	v_lshlrev_b32_e32 v151, 7, v150
	v_lshl_add_u64 v[122:123], s[84:85], 0, v[122:123]
	v_and_b32_e32 v138, 0x2780, v151
	v_cvt_pk_bf16_f32 v127, v160, v161
	v_lshl_add_u64 v[160:161], v[122:123], 0, v[138:139]
	v_mov_b32_e32 v149, v139
	v_max_f32_e32 v119, 0, v119
	v_max_f32_e32 v118, 0, v118
	s_or_b32 s28, s26, 2
	v_lshl_add_u64 v[160:161], v[160:161], 0, v[148:149]
	v_max_f32_e32 v115, 0, v115
	v_max_f32_e32 v114, 0, v114
	v_max_f32_e32 v117, 0, v117
	v_max_f32_e32 v116, 0, v116
	v_pk_mul_f32 v[118:119], v[118:119], v[118:119]
	s_ashr_i32 s29, s28, 31
	global_store_dwordx4 v[160:161], v[124:127], off
	s_nop 1
	v_pk_mul_f32 v[124:125], v[116:117], v[116:117]
	v_pk_mul_f32 v[116:117], v[114:115], v[114:115]
	v_cvt_pk_bf16_f32 v114, v118, v119
	v_lshl_add_u64 v[118:119], v[128:129], 0, s[28:29]
	v_max_f32_e32 v121, 0, v121
	v_max_f32_e32 v120, 0, v120
	v_lshlrev_b64 v[118:119], 14, v[118:119]
	v_pk_mul_f32 v[120:121], v[120:121], v[120:121]
	v_lshl_add_u64 v[118:119], s[84:85], 0, v[118:119]
	v_cvt_pk_bf16_f32 v115, v120, v121
	v_lshl_add_u64 v[120:121], v[118:119], 0, v[138:139]
	v_max_f32_e32 v111, 0, v111
	v_max_f32_e32 v110, 0, v110
	v_cvt_pk_bf16_f32 v116, v116, v117
	v_cvt_pk_bf16_f32 v117, v124, v125
	v_lshl_add_u64 v[120:121], v[120:121], 0, v[148:149]
	v_max_f32_e32 v113, 0, v113
	v_max_f32_e32 v112, 0, v112
	v_max_f32_e32 v107, 0, v107
	v_max_f32_e32 v106, 0, v106
	v_max_f32_e32 v109, 0, v109
	v_max_f32_e32 v108, 0, v108
	v_pk_mul_f32 v[110:111], v[110:111], v[110:111]
	v_bitop3_b32 v138, v151, s55, v157 bitop3:0xc8
	global_store_dwordx4 v[120:121], v[114:117], off
	v_pk_mul_f32 v[112:113], v[112:113], v[112:113]
	v_max_f32_e32 v103, 0, v103
	v_pk_mul_f32 v[114:115], v[108:109], v[108:109]
	v_pk_mul_f32 v[108:109], v[106:107], v[106:107]
	v_cvt_pk_bf16_f32 v106, v110, v111
	v_lshl_add_u64 v[110:111], v[122:123], 0, v[138:139]
	v_max_f32_e32 v102, 0, v102
	v_cvt_pk_bf16_f32 v107, v112, v113
	v_cvt_pk_bf16_f32 v108, v108, v109
	v_cvt_pk_bf16_f32 v109, v114, v115
	v_lshl_add_u64 v[110:111], v[110:111], 0, v[148:149]
	v_max_f32_e32 v105, 0, v105
	v_max_f32_e32 v104, 0, v104
	v_max_f32_e32 v99, 0, v99
	v_max_f32_e32 v98, 0, v98
	v_max_f32_e32 v101, 0, v101
	v_max_f32_e32 v100, 0, v100
	v_pk_mul_f32 v[102:103], v[102:103], v[102:103]
	global_store_dwordx4 v[110:111], v[106:109], off
	v_pk_mul_f32 v[104:105], v[104:105], v[104:105]
	v_max_f32_e32 v95, 0, v95
	v_pk_mul_f32 v[106:107], v[100:101], v[100:101]
	v_pk_mul_f32 v[100:101], v[98:99], v[98:99]
	v_cvt_pk_bf16_f32 v98, v102, v103
	v_lshl_add_u64 v[102:103], v[118:119], 0, v[138:139]
	v_max_f32_e32 v94, 0, v94
	v_cvt_pk_bf16_f32 v99, v104, v105
	v_cvt_pk_bf16_f32 v100, v100, v101
	v_cvt_pk_bf16_f32 v101, v106, v107
	v_lshl_add_u64 v[102:103], v[102:103], 0, v[148:149]
	v_max_f32_e32 v97, 0, v97
	v_max_f32_e32 v96, 0, v96
	v_max_f32_e32 v91, 0, v91
	v_max_f32_e32 v90, 0, v90
	v_max_f32_e32 v93, 0, v93
	v_max_f32_e32 v92, 0, v92
	v_pk_mul_f32 v[94:95], v[94:95], v[94:95]
	v_bitop3_b32 v138, v151, s55, v158 bitop3:0xc8
	global_store_dwordx4 v[102:103], v[98:101], off
	v_pk_mul_f32 v[96:97], v[96:97], v[96:97]
	v_max_f32_e32 v87, 0, v87
	v_pk_mul_f32 v[98:99], v[92:93], v[92:93]
	v_pk_mul_f32 v[92:93], v[90:91], v[90:91]
	v_cvt_pk_bf16_f32 v90, v94, v95
	v_lshl_add_u64 v[94:95], v[122:123], 0, v[138:139]
	v_max_f32_e32 v86, 0, v86
	v_cvt_pk_bf16_f32 v91, v96, v97
	v_cvt_pk_bf16_f32 v92, v92, v93
	v_cvt_pk_bf16_f32 v93, v98, v99
	v_lshl_add_u64 v[94:95], v[94:95], 0, v[148:149]
	v_max_f32_e32 v89, 0, v89
	v_max_f32_e32 v88, 0, v88
	v_max_f32_e32 v83, 0, v83
	v_max_f32_e32 v82, 0, v82
	v_max_f32_e32 v85, 0, v85
	v_max_f32_e32 v84, 0, v84
	v_pk_mul_f32 v[86:87], v[86:87], v[86:87]
	global_store_dwordx4 v[94:95], v[90:93], off
	v_pk_mul_f32 v[88:89], v[88:89], v[88:89]
	v_max_f32_e32 v79, 0, v79
	v_pk_mul_f32 v[90:91], v[84:85], v[84:85]
	v_pk_mul_f32 v[84:85], v[82:83], v[82:83]
	v_cvt_pk_bf16_f32 v82, v86, v87
	v_lshl_add_u64 v[86:87], v[118:119], 0, v[138:139]
	v_max_f32_e32 v78, 0, v78
	v_cvt_pk_bf16_f32 v83, v88, v89
	v_cvt_pk_bf16_f32 v84, v84, v85
	v_cvt_pk_bf16_f32 v85, v90, v91
	v_lshl_add_u64 v[86:87], v[86:87], 0, v[148:149]
	v_max_f32_e32 v81, 0, v81
	v_max_f32_e32 v80, 0, v80
	v_max_f32_e32 v75, 0, v75
	v_max_f32_e32 v74, 0, v74
	v_max_f32_e32 v77, 0, v77
	v_max_f32_e32 v76, 0, v76
	v_pk_mul_f32 v[78:79], v[78:79], v[78:79]
	v_bitop3_b32 v138, v151, s55, v159 bitop3:0xc8
	global_store_dwordx4 v[86:87], v[82:85], off
	v_pk_mul_f32 v[80:81], v[80:81], v[80:81]
	v_max_f32_e32 v71, 0, v71
	v_pk_mul_f32 v[82:83], v[76:77], v[76:77]
	v_pk_mul_f32 v[76:77], v[74:75], v[74:75]
	v_cvt_pk_bf16_f32 v74, v78, v79
	v_lshl_add_u64 v[78:79], v[122:123], 0, v[138:139]
	v_max_f32_e32 v70, 0, v70
	v_cvt_pk_bf16_f32 v75, v80, v81
	v_cvt_pk_bf16_f32 v76, v76, v77
	v_cvt_pk_bf16_f32 v77, v82, v83
	v_lshl_add_u64 v[78:79], v[78:79], 0, v[148:149]
	v_max_f32_e32 v73, 0, v73
	v_max_f32_e32 v72, 0, v72
	v_max_f32_e32 v67, 0, v67
	v_max_f32_e32 v66, 0, v66
	v_max_f32_e32 v69, 0, v69
	v_max_f32_e32 v68, 0, v68
	v_pk_mul_f32 v[70:71], v[70:71], v[70:71]
	global_store_dwordx4 v[78:79], v[74:77], off
	s_nop 0
	v_pk_mul_f32 v[72:73], v[72:73], v[72:73]
	v_pk_mul_f32 v[74:75], v[68:69], v[68:69]
	v_pk_mul_f32 v[68:69], v[66:67], v[66:67]
	v_cvt_pk_bf16_f32 v66, v70, v71
	v_lshl_add_u64 v[70:71], v[118:119], 0, v[138:139]
	v_cvt_pk_bf16_f32 v67, v72, v73
	v_cvt_pk_bf16_f32 v68, v68, v69
	v_cvt_pk_bf16_f32 v69, v74, v75
	v_lshl_add_u64 v[70:71], v[70:71], 0, v[148:149]
	global_store_dwordx4 v[70:71], v[66:69], off
	v_max_f32_e32 v63, 0, v63
	v_max_f32_e32 v62, 0, v62
	v_add_u32_e32 v66, 0x80, v150
	v_ashrrev_i32_e32 v67, 31, v66
	v_max_f32_e32 v59, 0, v59
	v_max_f32_e32 v58, 0, v58
	v_max_f32_e32 v61, 0, v61
	v_max_f32_e32 v60, 0, v60
	v_pk_mul_f32 v[62:63], v[62:63], v[62:63]
	v_max_f32_e32 v65, 0, v65
	v_max_f32_e32 v64, 0, v64
	v_pk_mul_f32 v[68:69], v[60:61], v[60:61]
	v_pk_mul_f32 v[60:61], v[58:59], v[58:59]
	v_cvt_pk_bf16_f32 v58, v62, v63
	v_lshlrev_b64 v[62:63], 1, v[66:67]
	v_pk_mul_f32 v[64:65], v[64:65], v[64:65]
	v_and_b32_e32 v62, 0xffffff00, v62
	v_cvt_pk_bf16_f32 v59, v64, v65
	v_lshl_add_u64 v[64:65], v[62:63], 0, s[26:27]
	v_lshlrev_b64 v[64:65], 14, v[64:65]
	v_lshlrev_b32_e32 v66, 7, v66
	v_lshl_add_u64 v[64:65], s[84:85], 0, v[64:65]
	v_and_b32_e32 v138, 0x3f80, v66
	v_lshl_add_u64 v[64:65], v[64:65], 0, v[138:139]
	v_max_f32_e32 v55, 0, v55
	v_max_f32_e32 v54, 0, v54
	v_cvt_pk_bf16_f32 v60, v60, v61
	v_cvt_pk_bf16_f32 v61, v68, v69
	v_lshl_add_u64 v[64:65], v[64:65], 0, v[148:149]
	v_max_f32_e32 v51, 0, v51
	v_max_f32_e32 v50, 0, v50
	v_max_f32_e32 v53, 0, v53
	v_max_f32_e32 v52, 0, v52
	v_pk_mul_f32 v[54:55], v[54:55], v[54:55]
	global_store_dwordx4 v[64:65], v[58:61], off
	s_nop 1
	v_pk_mul_f32 v[58:59], v[52:53], v[52:53]
	v_pk_mul_f32 v[52:53], v[50:51], v[50:51]
	v_cvt_pk_bf16_f32 v50, v54, v55
	v_lshl_add_u64 v[54:55], v[62:63], 0, s[28:29]
	v_lshlrev_b64 v[54:55], 14, v[54:55]
	v_max_f32_e32 v57, 0, v57
	v_max_f32_e32 v56, 0, v56
	v_lshl_add_u64 v[54:55], s[84:85], 0, v[54:55]
	v_pk_mul_f32 v[56:57], v[56:57], v[56:57]
	v_lshl_add_u64 v[54:55], v[54:55], 0, v[138:139]
	v_cvt_pk_bf16_f32 v51, v56, v57
	v_cvt_pk_bf16_f32 v52, v52, v53
	v_cvt_pk_bf16_f32 v53, v58, v59
	v_lshl_add_u64 v[54:55], v[54:55], 0, v[148:149]
	global_store_dwordx4 v[54:55], v[50:53], off
	v_max_f32_e32 v47, 0, v47
	v_max_f32_e32 v46, 0, v46
	v_add_u32_e32 v50, 0x90, v150
	v_ashrrev_i32_e32 v51, 31, v50
	v_max_f32_e32 v43, 0, v43
	v_max_f32_e32 v42, 0, v42
	v_max_f32_e32 v45, 0, v45
	v_max_f32_e32 v44, 0, v44
	v_pk_mul_f32 v[46:47], v[46:47], v[46:47]
	v_max_f32_e32 v49, 0, v49
	v_max_f32_e32 v48, 0, v48
	v_pk_mul_f32 v[52:53], v[44:45], v[44:45]
	v_pk_mul_f32 v[44:45], v[42:43], v[42:43]
	v_cvt_pk_bf16_f32 v42, v46, v47
	v_lshlrev_b64 v[46:47], 1, v[50:51]
	v_pk_mul_f32 v[48:49], v[48:49], v[48:49]
	v_and_b32_e32 v46, 0xffffff00, v46
	v_cvt_pk_bf16_f32 v43, v48, v49
	v_lshl_add_u64 v[48:49], v[46:47], 0, s[26:27]
	v_lshlrev_b64 v[48:49], 14, v[48:49]
	v_lshlrev_b32_e32 v50, 7, v50
	v_lshl_add_u64 v[48:49], s[84:85], 0, v[48:49]
	v_and_b32_e32 v138, 0x3f80, v50
	v_lshl_add_u64 v[48:49], v[48:49], 0, v[138:139]
	v_max_f32_e32 v39, 0, v39
	v_max_f32_e32 v38, 0, v38
	v_cvt_pk_bf16_f32 v44, v44, v45
	v_cvt_pk_bf16_f32 v45, v52, v53
	v_lshl_add_u64 v[48:49], v[48:49], 0, v[148:149]
	v_max_f32_e32 v35, 0, v35
	v_max_f32_e32 v34, 0, v34
	v_max_f32_e32 v37, 0, v37
	v_max_f32_e32 v36, 0, v36
	v_pk_mul_f32 v[38:39], v[38:39], v[38:39]
	global_store_dwordx4 v[48:49], v[42:45], off
	s_nop 1
	v_pk_mul_f32 v[42:43], v[36:37], v[36:37]
	v_pk_mul_f32 v[36:37], v[34:35], v[34:35]
	v_cvt_pk_bf16_f32 v34, v38, v39
	v_lshl_add_u64 v[38:39], v[46:47], 0, s[28:29]
	v_lshlrev_b64 v[38:39], 14, v[38:39]
	v_max_f32_e32 v41, 0, v41
	v_max_f32_e32 v40, 0, v40
	v_lshl_add_u64 v[38:39], s[84:85], 0, v[38:39]
	v_pk_mul_f32 v[40:41], v[40:41], v[40:41]
	v_lshl_add_u64 v[38:39], v[38:39], 0, v[138:139]
	v_cvt_pk_bf16_f32 v35, v40, v41
	v_cvt_pk_bf16_f32 v36, v36, v37
	v_cvt_pk_bf16_f32 v37, v42, v43
	v_lshl_add_u64 v[38:39], v[38:39], 0, v[148:149]
	global_store_dwordx4 v[38:39], v[34:37], off
	v_max_f32_e32 v31, 0, v31
	v_max_f32_e32 v30, 0, v30
	v_add_u32_e32 v34, 0xa0, v150
	v_ashrrev_i32_e32 v35, 31, v34
	v_max_f32_e32 v27, 0, v27
	v_max_f32_e32 v26, 0, v26
	v_max_f32_e32 v29, 0, v29
	v_max_f32_e32 v28, 0, v28
	v_pk_mul_f32 v[30:31], v[30:31], v[30:31]
	v_max_f32_e32 v33, 0, v33
	v_max_f32_e32 v32, 0, v32
	v_pk_mul_f32 v[36:37], v[28:29], v[28:29]
	v_pk_mul_f32 v[28:29], v[26:27], v[26:27]
	v_cvt_pk_bf16_f32 v26, v30, v31
	v_lshlrev_b64 v[30:31], 1, v[34:35]
	v_pk_mul_f32 v[32:33], v[32:33], v[32:33]
	v_and_b32_e32 v30, 0xffffff00, v30
	v_cvt_pk_bf16_f32 v27, v32, v33
	v_lshl_add_u64 v[32:33], v[30:31], 0, s[26:27]
	v_lshlrev_b64 v[32:33], 14, v[32:33]
	v_lshlrev_b32_e32 v34, 7, v34
	v_lshl_add_u64 v[32:33], s[84:85], 0, v[32:33]
	v_and_b32_e32 v138, 0x3f80, v34
	v_lshl_add_u64 v[32:33], v[32:33], 0, v[138:139]
	v_max_f32_e32 v23, 0, v23
	v_max_f32_e32 v22, 0, v22
	v_cvt_pk_bf16_f32 v28, v28, v29
	v_cvt_pk_bf16_f32 v29, v36, v37
	v_lshl_add_u64 v[32:33], v[32:33], 0, v[148:149]
	v_max_f32_e32 v19, 0, v19
	v_max_f32_e32 v18, 0, v18
	v_max_f32_e32 v21, 0, v21
	v_max_f32_e32 v20, 0, v20
	v_pk_mul_f32 v[22:23], v[22:23], v[22:23]
	global_store_dwordx4 v[32:33], v[26:29], off
	s_nop 1
	v_pk_mul_f32 v[26:27], v[20:21], v[20:21]
	v_pk_mul_f32 v[20:21], v[18:19], v[18:19]
	v_cvt_pk_bf16_f32 v18, v22, v23
	v_lshl_add_u64 v[22:23], v[30:31], 0, s[28:29]
	v_lshlrev_b64 v[22:23], 14, v[22:23]
	v_max_f32_e32 v25, 0, v25
	v_max_f32_e32 v24, 0, v24
	v_lshl_add_u64 v[22:23], s[84:85], 0, v[22:23]
	v_pk_mul_f32 v[24:25], v[24:25], v[24:25]
	v_lshl_add_u64 v[22:23], v[22:23], 0, v[138:139]
	v_cvt_pk_bf16_f32 v19, v24, v25
	v_cvt_pk_bf16_f32 v20, v20, v21
	v_cvt_pk_bf16_f32 v21, v26, v27
	v_lshl_add_u64 v[22:23], v[22:23], 0, v[148:149]
	global_store_dwordx4 v[22:23], v[18:21], off
	v_max_f32_e32 v15, 0, v15
	v_max_f32_e32 v14, 0, v14
	v_add_u32_e32 v18, 0xb0, v150
	v_ashrrev_i32_e32 v19, 31, v18
	v_max_f32_e32 v11, 0, v11
	v_max_f32_e32 v10, 0, v10
	v_max_f32_e32 v13, 0, v13
	v_max_f32_e32 v12, 0, v12
	v_pk_mul_f32 v[14:15], v[14:15], v[14:15]
	v_max_f32_e32 v17, 0, v17
	v_max_f32_e32 v16, 0, v16
	v_pk_mul_f32 v[20:21], v[12:13], v[12:13]
	v_pk_mul_f32 v[12:13], v[10:11], v[10:11]
	v_cvt_pk_bf16_f32 v10, v14, v15
	v_lshlrev_b64 v[14:15], 1, v[18:19]
	v_pk_mul_f32 v[16:17], v[16:17], v[16:17]
	v_and_b32_e32 v14, 0xffffff00, v14
	v_cvt_pk_bf16_f32 v11, v16, v17
	v_lshl_add_u64 v[16:17], v[14:15], 0, s[26:27]
	v_lshlrev_b64 v[16:17], 14, v[16:17]
	v_lshlrev_b32_e32 v18, 7, v18
	v_lshl_add_u64 v[16:17], s[84:85], 0, v[16:17]
	v_and_b32_e32 v138, 0x3f80, v18
	v_lshl_add_u64 v[16:17], v[16:17], 0, v[138:139]
	v_max_f32_e32 v7, 0, v7
	v_max_f32_e32 v6, 0, v6
	v_cvt_pk_bf16_f32 v12, v12, v13
	v_cvt_pk_bf16_f32 v13, v20, v21
	v_lshl_add_u64 v[16:17], v[16:17], 0, v[148:149]
	v_max_f32_e32 v3, 0, v3
	v_max_f32_e32 v2, 0, v2
	v_max_f32_e32 v5, 0, v5
	v_max_f32_e32 v4, 0, v4
	v_pk_mul_f32 v[6:7], v[6:7], v[6:7]
	global_store_dwordx4 v[16:17], v[10:13], off
	s_nop 1
	v_pk_mul_f32 v[10:11], v[4:5], v[4:5]
	v_pk_mul_f32 v[4:5], v[2:3], v[2:3]
	v_cvt_pk_bf16_f32 v2, v6, v7
	v_lshl_add_u64 v[6:7], v[14:15], 0, s[28:29]
	v_lshlrev_b64 v[6:7], 14, v[6:7]
	v_max_f32_e32 v9, 0, v9
	v_max_f32_e32 v8, 0, v8
	v_lshl_add_u64 v[6:7], s[84:85], 0, v[6:7]
	v_pk_mul_f32 v[8:9], v[8:9], v[8:9]
	v_lshl_add_u64 v[6:7], v[6:7], 0, v[138:139]
	v_cvt_pk_bf16_f32 v3, v8, v9
	v_cvt_pk_bf16_f32 v4, v4, v5
	v_cvt_pk_bf16_f32 v5, v10, v11
	v_lshl_add_u64 v[6:7], v[6:7], 0, v[148:149]
	s_andn2_b64 vcc, exec, s[4:5]
	s_mov_b64 s[4:5], -1
	global_store_dwordx4 v[6:7], v[2:5], off
	s_cbranch_vccnz .LBB0_1207
	s_andn2_b64 vcc, exec, s[6:7]
	s_cbranch_vccnz .LBB0_1206
	s_barrier
	s_branch .LBB0_1206
